# dependency counters sampled next to the barrier arrival atomic (the later flag wait usually finds them complete)
# speedup vs baseline: 1.0136x; 1.0022x over previous
.LBB0_261:
	s_or_b64 exec, exec, s[6:7]
	s_and_b32 s98, s64, 127
	s_lshr_b32 s98, s98, 1
	s_max_u32 s99, s98, 1
	s_add_i32 s99, s99, -1
	s_lshl_b32 s98, s98, 8
	s_lshl_b32 s99, s99, 8
	s_add_i32 s98, s98, 0x8000
	s_add_i32 s99, s99, 0x8000
	v_mov_b32_e32 v250, s98
	v_mov_b32_e32 v251, s99
	global_load_dword v250, v250, s[82:83] sc1
	global_load_dword v251, v251, s[82:83] sc1
	v_cvt_f32_u32_e32 v6, v4
	s_waitcnt vmcnt(0)
	v_readfirstlane_b32 s4, v5
	v_sub_u32_e32 v5, 0, v4
	v_rcp_iflag_f32_e32 v6, v6
	v_add_u32_e32 v7, s4, v3
	v_mul_f32_e32 v6, 0x4f7ffffe, v6
	v_cvt_u32_f32_e32 v6, v6
	v_mul_lo_u32 v3, v5, v6
	v_mul_hi_u32 v3, v6, v3
	v_add_u32_e32 v3, v6, v3
	v_mul_hi_u32 v3, v7, v3
	v_mul_lo_u32 v5, v3, v4
	v_sub_u32_e32 v5, v7, v5
	v_add_u32_e32 v6, 1, v3
	v_cmp_ge_u32_e32 vcc, v5, v4
	s_nop 1
	v_cndmask_b32_e32 v3, v3, v6, vcc
	v_sub_u32_e32 v6, v5, v4
	v_cndmask_b32_e32 v5, v5, v6, vcc
	v_add_u32_e32 v6, 1, v3
	v_cmp_ge_u32_e32 vcc, v5, v4
	v_add_u32_e32 v5, 1, v7
	s_nop 0
	v_cndmask_b32_e32 v3, v3, v6, vcc
	v_mul_lo_u32 v6, v4, v3
	v_add_u32_e32 v4, v6, v4
	v_cmp_ne_u32_e32 vcc, v5, v4
	s_and_saveexec_b64 s[4:5], vcc
	s_xor_b64 s[4:5], exec, s[4:5]
	s_cbranch_execz .LBB0_275
	s_waitcnt lgkmcnt(0)
	v_mov_b32_e32 v2, 0x7000
	buffer_inv sc1
	s_branch .Lsplit3_nl
	global_load_dword v2, v2, s[82:83] offset:1280 sc1
	s_add_u32 s10, s82, 0x7500
	s_addc_u32 s11, s83, 0
	s_waitcnt vmcnt(0)
	v_cmp_eq_u32_e32 vcc, v2, v3
	s_and_saveexec_b64 s[6:7], vcc
	s_cbranch_execz .LBB0_274
	s_add_u32 s8, s82, 0x4200
	s_addc_u32 s9, s83, 0
	s_mov_b32 s22, 1
	s_mov_b64 s[12:13], 0
	v_mov_b32_e32 v2, 0
	s_branch .LBB0_265

.LBB0_295:
	s_or_b64 exec, exec, s[0:1]
	v_mov_b32_e32 v12, v0
	s_waitcnt lgkmcnt(0)
	s_barrier
	s_mov_b64 s[100:101], exec
	v_readlane_b32 s98, v254, 6
	s_nop 3
	s_mov_b32 exec_lo, s98
	s_mov_b32 exec_hi, 0
	s_cbranch_execz .Lp3dep_join
	s_and_b32 s98, s64, 127
	s_lshr_b32 s98, s98, 1
	s_max_u32 s99, s98, 1
	s_add_i32 s99, s99, -1
	s_lshl_b32 s98, s98, 8
	s_lshl_b32 s99, s99, 8
	s_add_i32 s98, s98, 0x8000
	s_add_i32 s99, s99, 0x8000
	v_mov_b32_e32 v240, s98
	v_mov_b32_e32 v241, s99
	v_mov_b32_e32 v244, 0
	v_readfirstlane_b32 s98, v250
	v_readfirstlane_b32 s99, v251
	s_nop 3
	s_cmp_lt_u32 s98, 6
	s_cbranch_scc1 .Lp3dep_spin
	s_cmp_ge_u32 s99, 6
	s_cbranch_scc1 .Lp3dep_join

.LBB0_634:
	s_or_b64 exec, exec, s[6:7]
	s_lshr_b32 s98, s64, 5
	s_and_b32 s98, s98, 3
	s_lshl_b32 s98, s98, 8
	s_add_i32 s99, s98, 0x18000
	s_add_i32 s98, s98, 0x19000
	v_mov_b32_e32 v250, s98
	v_mov_b32_e32 v251, s99
	global_load_dword v252, v250, s[82:83] offset:1024 sc1
	global_load_dword v250, v250, s[82:83] sc1
	global_load_dword v251, v251, s[82:83] sc1
	v_cvt_f32_u32_e32 v6, v4
	s_waitcnt vmcnt(0)
	v_readfirstlane_b32 s4, v5
	v_sub_u32_e32 v5, 0, v4
	v_rcp_iflag_f32_e32 v6, v6
	v_add_u32_e32 v7, s4, v3
	v_mul_f32_e32 v6, 0x4f7ffffe, v6
	v_cvt_u32_f32_e32 v6, v6
	v_mul_lo_u32 v3, v5, v6
	v_mul_hi_u32 v3, v6, v3
	v_add_u32_e32 v3, v6, v3
	v_mul_hi_u32 v3, v7, v3
	v_mul_lo_u32 v5, v3, v4
	v_sub_u32_e32 v5, v7, v5
	v_add_u32_e32 v6, 1, v3
	v_cmp_ge_u32_e32 vcc, v5, v4
	s_nop 1
	v_cndmask_b32_e32 v3, v3, v6, vcc
	v_sub_u32_e32 v6, v5, v4
	v_cndmask_b32_e32 v5, v5, v6, vcc
	v_add_u32_e32 v6, 1, v3
	v_cmp_ge_u32_e32 vcc, v5, v4
	v_add_u32_e32 v5, 1, v7
	s_nop 0
	v_cndmask_b32_e32 v3, v3, v6, vcc
	v_mul_lo_u32 v6, v4, v3
	v_add_u32_e32 v4, v6, v4
	v_cmp_ne_u32_e32 vcc, v5, v4
	s_and_saveexec_b64 s[4:5], vcc
	s_xor_b64 s[4:5], exec, s[4:5]
	s_cbranch_execz .LBB0_793
	s_waitcnt lgkmcnt(0)
	v_mov_b32_e32 v2, 0x7000
	buffer_inv sc1
	s_cmpk_gt_u32 s64, 0x7f
	s_branch .Lsplit5_nl
	global_load_dword v2, v2, s[82:83] offset:1280 sc1
	s_add_u32 s10, s82, 0x7500
	s_addc_u32 s11, s83, 0
	s_waitcnt vmcnt(0)
	v_cmp_eq_u32_e32 vcc, v2, v3
	s_and_saveexec_b64 s[6:7], vcc
	s_cbranch_execz .LBB0_792
	s_add_u32 s8, s82, 0x4200
	s_addc_u32 s9, s83, 0
	s_mov_b32 s22, 1
	s_mov_b64 s[12:13], 0
	v_mov_b32_e32 v2, 0
	s_branch .LBB0_638

.LBB0_871:
	s_and_b64 vcc, exec, s[0:1]
	v_readlane_b32 s53, v254, 2
	s_cbranch_vccz .LBB0_900
	s_mov_b64 s[100:101], exec
	v_readlane_b32 s98, v254, 6
	s_nop 3
	s_mov_b32 exec_lo, s98
	s_mov_b32 exec_hi, 0
	s_cbranch_execz .Ll3dep_join
	s_lshr_b32 s98, s64, 5
	s_lshl_b32 s98, s98, 8
	s_add_i32 s99, s98, 0x18000
	s_add_i32 s98, s98, 0x19000
	v_mov_b32_e32 v240, s98
	v_mov_b32_e32 v241, s99
	v_mov_b32_e32 v244, 0
	v_readfirstlane_b32 s98, v250
	v_readfirstlane_b32 s99, v251
	s_nop 3
	s_cmp_lt_u32 s98, 4
	s_cbranch_scc1 .Ll3dep_spin
	s_cmp_lt_u32 s99, 30
	s_cbranch_scc1 .Ll3dep_spin
	v_readfirstlane_b32 s98, v252
	s_nop 3
	s_cmp_ge_u32 s98, 2
	s_cbranch_scc1 .Ll3dep_join
